# as S12 with the second half of the K-fragment LDS reads also issued inside the QK MFMA block (smaller read burst after the barrier)
# speedup vs baseline: 1.0029x; 1.0029x over previous
; __device__ __forceinline__ void finishSM(f32x16& p0, f32x16& p1, float alpha, float& l_reg, bf16x8& pa0, bf16x8& pa1, bf16x8& pa2, bf16x8& pa3) {
;   for (int r = 0; r < 16; ++r) p1[r] = __builtin_amdgcn_exp2f(p1[r]);
;   float ps = 0; for (int r = 0; r < 16; ++r) ps += p0[r]; for (int r = 0; r < 16; ++r) ps += p1[r];
;   { auto rr = __builtin_amdgcn_permlane32_swap(__float_as_uint(ps), __float_as_uint(ps), false, false);
;     ps = __uint_as_float(rr[0]) + __uint_as_float(rr[1]); }
;   l_reg = l_reg * alpha + ps;
;     ...
;   PK4(p0, 0, pa0); PK4(p0, 8, pa1); PK4(p1, 0, pa2); PK4(p1, 8, pa3);
;     ...
; }
; __device__ __forceinline__ void kload(bf16x8 (&kf)[8], const char* Ks, int r32, int hi, int sb) {
; #pragma unroll
;   for (int d0 = 0; d0 < 4; ++d0) { const int cb = sb + (d0 * 16 + hi * 8) * 2;
;     kf[2 * d0] = *reinterpret_cast<const bf16x8*>(Ks + KSWZ(r32, cb)); kf[2 * d0 + 1] = *reinterpret_cast<const bf16x8*>(Ks + KSWZ(32 + r32, cb)); }
; }
; __device__ __forceinline__ void kmma(f32x16& p0, f32x16& p1, const bf16x8 (&kf)[8], const bf16x8* qr) {
;   asm volatile("s_waitcnt lgkmcnt(0)" ::: "memory"); SBAR();
;   p0 = f32x16{}; p1 = f32x16{};
; #pragma unroll
;   for (int d0 = 0; d0 < 4; ++d0) { p0 = __builtin_amdgcn_mfma_f32_32x32x16_bf16(kf[2 * d0], qr[d0], p0, 0, 0, 0); p1 = __builtin_amdgcn_mfma_f32_32x32x16_bf16(kf[2 * d0 + 1], qr[d0], p1, 0, 0, 0); }
; }
; __device__ __forceinline__ void qkt(f32x16& p0, f32x16& p1, const char* Ks, const bf16x8* qr, int r32, int hi, int sb) {
;   bf16x8 kf[8]; kload(kf, Ks, r32, hi, sb); SBAR(); kmma(p0, p1, kf, qr);
; }
; __device__ __forceinline__ int v_st(int k, int c) { const int kk = (k & ~0xC) | ((k & 4) << 1) | ((k & 8) >> 1); return ((kk >> 3) * 4 + (c >> 5)) * 512 + ((kk & 7) * 32 + (c & 31)) * 2; }
; __device__ __forceinline__ int v_rd_base(int lane) { return ((lane & 3) << 3) | (((lane >> 2) & 3) << 6) | (((lane >> 4) & 1) << 5) | (((lane >> 5) & 1) << 8); }
; template <int OFF> __device__ __forceinline__ s16x4 tr_read(int vb) {
;   s16x4 r; asm volatile("ds_read_b64_tr_b16 %0, %1 offset:%2" : "=&v"(r) : "v"(vb), "i"(OFF) : "memory"); return r;
; }
; template <int D0> __device__ __forceinline__ void v_frag_read(VFrag& f, int vb) {
;   f.l0 = tr_read<v_rd_off(D0, 0, 0)>(vb); f.h0 = tr_read<v_rd_off(D0, 0, 1)>(vb); f.l1 = tr_read<v_rd_off(D0, 1, 0)>(vb); f.h1 = tr_read<v_rd_off(D0, 1, 1)>(vb);
.LBB0_770:
	ds_read_b128 v[82:85], v245
	ds_read_b128 v[86:89], v245 offset:8192
	ds_read_b128 v[130:133], v246
	ds_read_b128 v[134:137], v246 offset:8192
	v_exp_f32_e32 v148, v66
	v_add_f32_e32 v66, 0, v175
	v_add_f32_e32 v66, v177, v66
	v_add_f32_e32 v66, v192, v66
	v_add_f32_e32 v66, v195, v66
	v_add_f32_e32 v66, v196, v66
	v_add_f32_e32 v66, v199, v66
	v_add_f32_e32 v66, v200, v66
	v_add_f32_e32 v66, v203, v66
	v_add_f32_e32 v66, v176, v66
	v_add_f32_e32 v66, v193, v66
	v_add_f32_e32 v66, v194, v66
	v_add_f32_e32 v66, v197, v66
	v_add_f32_e32 v66, v198, v66
	v_exp_f32_e32 v149, v67
	v_add_f32_e32 v66, v201, v66
	s_waitcnt lgkmcnt(3)
	v_mfma_f32_32x32x16_bf16 v[98:113], v[82:85], v[126:129], 0
	v_exp_f32_e32 v150, v68
	v_add_f32_e32 v66, v202, v66
	ds_read_b128 v[206:209], v247
	v_exp_f32_e32 v151, v69
	ds_read_b128 v[210:213], v247 offset:8192
	v_add_f32_e32 v66, v204, v66
	ds_read_b128 v[214:217], v255
	ds_read_b128 v[218:221], v255 offset:8192
	s_and_b32 s13, s36, 0xc000
	s_waitcnt lgkmcnt(6)
	v_mfma_f32_32x32x16_bf16 v[82:97], v[86:89], v[126:129], 0
	v_exp_f32_e32 v186, v70
	v_add_u32_e32 v244, s13, v164
	v_add_f32_e32 v66, v148, v66
	ds_read_b64_tr_b16 v[228:229], v244 offset:0
	v_exp_f32_e32 v187, v71
	ds_read_b64_tr_b16 v[230:231], v244 offset:0x800
	v_add_f32_e32 v66, v149, v66
	ds_read_b64_tr_b16 v[232:233], v244 offset:0x1000
	v_exp_f32_e32 v188, v72
	ds_read_b64_tr_b16 v[234:235], v244 offset:0x1800
	ds_read_b64_tr_b16 v[236:237], v244 offset:0x2000
	ds_read_b64_tr_b16 v[238:239], v244 offset:0x2800
	ds_read_b64_tr_b16 v[240:241], v244 offset:0x3000
	s_waitcnt lgkmcnt(12)
	v_mfma_f32_32x32x16_bf16 v[98:113], v[130:133], v[122:125], v[98:113]
	v_add_f32_e32 v66, v150, v66
	ds_read_b64_tr_b16 v[242:243], v244 offset:0x3800
	v_exp_f32_e32 v189, v73
	s_add_i32 s37, s12, 2
	v_add_f32_e32 v66, v151, v66
	s_cmpk_lt_u32 s12, 0x7e
	v_exp_f32_e32 v205, v74
	s_cselect_b64 s[0:1], -1, 0
	s_and_b64 s[10:11], s[0:1], exec
	s_cselect_b32 s10, 0, 0xffffff80
	s_add_i32 s58, s37, s10
	s_waitcnt lgkmcnt(12)
	v_mfma_f32_32x32x16_bf16 v[82:97], v[134:137], v[122:125], v[82:97]
	v_add_f32_e32 v66, v186, v66
	s_and_b64 s[0:1], s[0:1], exec
	v_exp_f32_e32 v222, v75
	s_cselect_b32 s1, s9, s30
	v_add_f32_e32 v66, v187, v66
	s_cselect_b32 s0, s8, s26
	v_exp_f32_e32 v223, v76
	s_lshl_b64 s[10:11], s[58:59], 17
	v_add_f32_e32 v66, v188, v66
	s_lshl_b64 s[0:1], s[0:1], 11
	s_add_u32 s10, s10, s0
	s_addc_u32 s11, s11, s1
	s_add_u32 s0, s20, s10
	s_waitcnt lgkmcnt(11)
	v_mfma_f32_32x32x16_bf16 v[98:113], v[206:209], v[118:121], v[98:113]
	v_exp_f32_e32 v224, v77
	s_addc_u32 s1, s21, s11
	v_add_f32_e32 v66, v189, v66
	s_add_u32 s10, s22, s10
	v_exp_f32_e32 v225, v78
	s_addc_u32 s11, s23, s11
	v_add_f32_e32 v66, v205, v66
	s_and_b32 s13, s37, 0xff
	s_mulk_i32 s13, 0xab
	s_lshr_b32 s13, s13, 9
	s_mul_i32 s13, s13, 3
	s_waitcnt lgkmcnt(10)
	v_mfma_f32_32x32x16_bf16 v[82:97], v[210:213], v[118:121], v[82:97]
	v_exp_f32_e32 v226, v79
	s_sub_i32 s13, s37, s13
	v_add_f32_e32 v66, v222, v66
	s_and_b32 s13, s13, 0xff
	v_exp_f32_e32 v227, v80
	s_lshl_b32 s13, s13, 14
	s_mov_b32 s100, s13
	v_add_f32_e32 v66, v223, v66
	s_add_i32 s42, s36, 0xffffc000
	v_exp_f32_e32 v81, v81
	s_and_b32 s42, s42, 0xc000
	s_add_i32 s13, s13, s27
	s_add_i32 s42, s42, s31
	v_lshl_add_u64 v[246:247], s[0:1], 0, v[146:147]
	s_waitcnt lgkmcnt(9)
	v_mfma_f32_32x32x16_bf16 v[98:113], v[214:217], v[114:117], v[98:113]
	v_add_f32_e32 v66, v224, v66
	s_mov_b32 m0, s13
	v_add_f32_e32 v66, v225, v66
	s_nop 0
	v_add_f32_e32 v66, v226, v66
	global_load_lds_dwordx4 v[246:247], off
	v_add_f32_e32 v66, v227, v66
	v_lshl_add_u64 v[246:247], s[10:11], 0, v[142:143]
	s_mov_b32 m0, s42
	s_nop 0
	global_load_lds_dwordx4 v[246:247], off
	s_waitcnt lgkmcnt(8)
	v_mfma_f32_32x32x16_bf16 v[82:97], v[218:221], v[114:117], v[82:97]
	v_add_f32_e32 v130, v81, v66
	v_lshl_add_u64 v[246:247], s[0:1], 0, v[144:145]
	v_mov_b32_e32 v131, v130
	s_add_i32 m0, s13, 0x2000
	v_cvt_pk_bf16_f32 v66, v175, v177
	s_nop 0
	v_cvt_pk_bf16_f32 v67, v192, v195
	global_load_lds_dwordx4 v[246:247], off
	v_cvt_pk_bf16_f32 v68, v196, v199
	v_lshl_add_u64 v[246:247], s[10:11], 0, v[154:155]
	s_add_i32 m0, s42, 0x2000
	s_nop 0
	global_load_lds_dwordx4 v[246:247], off
	v_permlane32_swap_b32_e32 v130, v131
	v_cvt_pk_bf16_f32 v69, v200, v203
	v_permlane32_swap_b32_e32 v66, v68
	v_cvt_pk_bf16_f32 v70, v176, v193
	v_cvt_pk_bf16_f32 v71, v194, v197
	v_cvt_pk_bf16_f32 v72, v198, v201
	v_cvt_pk_bf16_f32 v73, v202, v204
	v_cvt_pk_bf16_f32 v74, v148, v149
	v_cvt_pk_bf16_f32 v75, v150, v151
	v_cvt_pk_bf16_f32 v76, v186, v187
	v_cvt_pk_bf16_f32 v77, v188, v189
	v_cvt_pk_bf16_f32 v78, v205, v222
	v_cvt_pk_bf16_f32 v79, v223, v224
	v_cvt_pk_bf16_f32 v80, v225, v226
	v_cvt_pk_bf16_f32 v81, v227, v81
	v_permlane32_swap_b32_e32 v67, v69
	v_permlane32_swap_b32_e32 v70, v72
	v_permlane32_swap_b32_e32 v71, v73
	v_permlane32_swap_b32_e32 v74, v76
	v_permlane32_swap_b32_e32 v75, v77
	v_permlane32_swap_b32_e32 v78, v80
	v_permlane32_swap_b32_e32 v79, v81
	ds_read_b64_tr_b16 v[204:205], v244 offset:0x200
	ds_read_b64_tr_b16 v[206:207], v244 offset:0xa00
	ds_read_b64_tr_b16 v[208:209], v244 offset:0x1200
	ds_read_b64_tr_b16 v[210:211], v244 offset:0x1a00
	ds_read_b64_tr_b16 v[212:213], v244 offset:0x2200
	ds_read_b64_tr_b16 v[214:215], v244 offset:0x2a00
	ds_read_b64_tr_b16 v[216:217], v244 offset:0x3200
	ds_read_b64_tr_b16 v[218:219], v244 offset:0x3a00
	s_waitcnt lgkmcnt(14)
	v_mfma_f32_32x32x16_bf16 v[18:33], v[66:69], v[228:231], v[18:33]
	v_max_f32_e32 v245, v99, v99
	v_max_f32_e32 v246, v98, v98
	v_max_f32_e32 v245, v246, v245
	v_max3_f32 v245, v245, v100, v101
	v_max3_f32 v245, v245, v102, v103
	v_max3_f32 v245, v245, v104, v105
	v_max3_f32 v245, v245, v106, v107
	v_max3_f32 v245, v245, v108, v109
	s_waitcnt lgkmcnt(12)
; #define SBAR() __builtin_amdgcn_sched_barrier(0)
; __device__ __forceinline__ void partialSM(f32x16& p0, f32x16& p1, float& m_reg, float& mn, float& alpha) {
;   constexpr float C = SCALE * 1.4426950408889634f;
;   float pmax = p0[0]; for (int r = 1; r < 16; ++r) pmax = fmaxf(pmax, p0[r]); for (int r = 0; r < 16; ++r) pmax = fmaxf(pmax, p1[r]);
;   { auto rr = __builtin_amdgcn_permlane32_swap(__float_as_uint(pmax), __float_as_uint(pmax), false, false);
;     pmax = fmaxf(__uint_as_float(rr[0]), __uint_as_float(rr[1])); }
;   if (__builtin_expect(__all(pmax - m_reg <= THR / SCALE), 1)) { mn = m_reg; alpha = 1.f; }
;   else { mn = fmaxf(m_reg, pmax); alpha = __builtin_amdgcn_exp2f((m_reg - mn) * C); m_reg = mn; }
;   float mnC = -mn * C;
;   for (int r = 0; r < 16; ++r) p0[r] = fmaf(p0[r], C, mnC); for (int r = 0; r < 16; ++r) p1[r] = fmaf(p1[r], C, mnC);
;   for (int r = 0; r < 16; ++r) p0[r] = __builtin_amdgcn_exp2f(p0[r]);
; }
; __device__ __forceinline__ void pv_d0(f32x16* o, int vb, bf16x8 pa0, bf16x8 pa1, bf16x8 pa2, bf16x8 pa3) {
;   VFrag fa, fb;
;   v_frag_read<0>(fa, vb);
;   asm volatile("s_waitcnt lgkmcnt(0)" ::: "memory"); SBAR();
;   v_frag_read<1>(fb, vb); SBAR();
;   pv_mma(o[0], fa, pa0, pa1, pa2, pa3); SBAR();
;   asm volatile("s_waitcnt lgkmcnt(0)" ::: "memory"); SBAR();
;   v_frag_read<2>(fa, vb); SBAR();
;   pv_mma(o[1], fb, pa0, pa1, pa2, pa3); SBAR();
;   asm volatile("s_waitcnt lgkmcnt(0)" ::: "memory"); SBAR();
;   v_frag_read<3>(fb, vb); SBAR();
;   pv_mma(o[2], fa, pa0, pa1, pa2, pa3); SBAR();
;   asm volatile("s_waitcnt lgkmcnt(0)" ::: "memory"); SBAR();
;   pv_mma(o[3], fb, pa0, pa1, pa2, pa3);
; }
	v_mfma_f32_32x32x16_bf16 v[18:33], v[70:73], v[232:235], v[18:33]
	v_max3_f32 v245, v245, v110, v111
	v_max3_f32 v245, v245, v112, v113
	v_max3_f32 v245, v245, v82, v83
	v_max3_f32 v245, v245, v84, v85
	v_max3_f32 v245, v245, v86, v87
	v_max3_f32 v245, v245, v88, v89
	v_max3_f32 v245, v245, v90, v91
	v_max3_f32 v245, v245, v92, v93
	s_waitcnt lgkmcnt(10)
	v_mfma_f32_32x32x16_bf16 v[18:33], v[74:77], v[236:239], v[18:33]
	v_max3_f32 v245, v245, v94, v95
	v_max3_f32 v245, v245, v96, v97
	v_mov_b32_e32 v246, v245
	s_nop 1
	v_permlane32_swap_b32_e32 v245, v246
	v_max_f32_e32 v246, v246, v246
	v_max_f32_e32 v245, v245, v245
	v_max_f32_e32 v245, v245, v246
	v_sub_f32_e32 v246, v245, v174
	s_waitcnt lgkmcnt(8)
	v_mfma_f32_32x32x16_bf16 v[18:33], v[78:81], v[240:243], v[18:33]
	v_cmp_ge_f32_e32 vcc, s63, v246
	v_max_f32_e32 v246, v174, v174
	v_max_f32_e32 v245, v246, v245
	v_sub_f32_e32 v246, v174, v245
	v_mul_f32_e32 v246, 0x3e38aa3b, v246
	v_exp_f32_e32 v246, v246
	s_cmp_eq_u64 vcc, exec
	s_cselect_b64 s[0:1], -1, 0
	v_cndmask_b32_e64 v132, v246, 1.0, s[0:1]
	ds_read_b64_tr_b16 v[228:229], v244 offset:0x400
	ds_read_b64_tr_b16 v[230:231], v244 offset:0xc00
	ds_read_b64_tr_b16 v[232:233], v244 offset:0x1400
	ds_read_b64_tr_b16 v[234:235], v244 offset:0x1c00
	ds_read_b64_tr_b16 v[236:237], v244 offset:0x2400
	ds_read_b64_tr_b16 v[238:239], v244 offset:0x2c00
	ds_read_b64_tr_b16 v[240:241], v244 offset:0x3400
	ds_read_b64_tr_b16 v[242:243], v244 offset:0x3c00
	v_cndmask_b32_e64 v133, v245, v174, s[0:1]
	v_mul_f32_e32 v148, 0xbe38aa3b, v133
	s_waitcnt lgkmcnt(14)
	v_mfma_f32_32x32x16_bf16 v[50:65], v[66:69], v[204:207], v[50:65]
	v_fmamk_f32 v98, v98, 0x3e38aa3b, v148
	v_fmamk_f32 v99, v99, 0x3e38aa3b, v148
	v_fmamk_f32 v100, v100, 0x3e38aa3b, v148
	v_fmamk_f32 v101, v101, 0x3e38aa3b, v148
	s_waitcnt lgkmcnt(12)
	v_mfma_f32_32x32x16_bf16 v[50:65], v[70:73], v[208:211], v[50:65]
	v_fmamk_f32 v102, v102, 0x3e38aa3b, v148
	v_fmamk_f32 v103, v103, 0x3e38aa3b, v148
	v_fmamk_f32 v104, v104, 0x3e38aa3b, v148
	v_fmamk_f32 v105, v105, 0x3e38aa3b, v148
	s_waitcnt lgkmcnt(10)
	v_mfma_f32_32x32x16_bf16 v[50:65], v[74:77], v[212:215], v[50:65]
	v_fmamk_f32 v106, v106, 0x3e38aa3b, v148
	v_fmamk_f32 v107, v107, 0x3e38aa3b, v148
	v_fmamk_f32 v108, v108, 0x3e38aa3b, v148
	v_fmamk_f32 v109, v109, 0x3e38aa3b, v148
	s_waitcnt lgkmcnt(8)
	v_mfma_f32_32x32x16_bf16 v[50:65], v[78:81], v[216:219], v[50:65]
	v_fmamk_f32 v110, v110, 0x3e38aa3b, v148
	v_fmamk_f32 v111, v111, 0x3e38aa3b, v148
	v_fmamk_f32 v112, v112, 0x3e38aa3b, v148
	v_fmamk_f32 v113, v113, 0x3e38aa3b, v148
	ds_read_b64_tr_b16 v[204:205], v244 offset:0x600
	ds_read_b64_tr_b16 v[206:207], v244 offset:0xe00
	ds_read_b64_tr_b16 v[208:209], v244 offset:0x1600
	ds_read_b64_tr_b16 v[210:211], v244 offset:0x1e00
	ds_read_b64_tr_b16 v[212:213], v244 offset:0x2600
	ds_read_b64_tr_b16 v[214:215], v244 offset:0x2e00
	ds_read_b64_tr_b16 v[216:217], v244 offset:0x3600
	ds_read_b64_tr_b16 v[218:219], v244 offset:0x3e00
	s_waitcnt lgkmcnt(14)
	v_mfma_f32_32x32x16_bf16 v[34:49], v[66:69], v[228:231], v[34:49]
	v_fmamk_f32 v82, v82, 0x3e38aa3b, v148
	v_fmamk_f32 v83, v83, 0x3e38aa3b, v148
	v_fmamk_f32 v84, v84, 0x3e38aa3b, v148
	v_fmamk_f32 v85, v85, 0x3e38aa3b, v148
	s_waitcnt lgkmcnt(12)
	v_mfma_f32_32x32x16_bf16 v[34:49], v[70:73], v[232:235], v[34:49]
	v_fmamk_f32 v86, v86, 0x3e38aa3b, v148
	v_fmamk_f32 v87, v87, 0x3e38aa3b, v148
	s_add_i32 s13, s36, 0xffff4000
	v_fmamk_f32 v149, v88, 0x3e38aa3b, v148
	s_waitcnt lgkmcnt(10)
	v_mfma_f32_32x32x16_bf16 v[34:49], v[74:77], v[236:239], v[34:49]
	v_fmamk_f32 v150, v89, 0x3e38aa3b, v148
	v_fmamk_f32 v151, v90, 0x3e38aa3b, v148
	v_fmamk_f32 v186, v91, 0x3e38aa3b, v148
	v_fmamk_f32 v187, v92, 0x3e38aa3b, v148
	s_waitcnt lgkmcnt(8)
	v_mfma_f32_32x32x16_bf16 v[34:49], v[78:81], v[240:243], v[34:49]
	v_fmamk_f32 v188, v93, 0x3e38aa3b, v148
	v_fmamk_f32 v189, v94, 0x3e38aa3b, v148
	v_exp_f32_e32 v192, v98
	v_exp_f32_e32 v193, v99
	v_exp_f32_e32 v194, v100
	v_exp_f32_e32 v195, v101
	s_waitcnt lgkmcnt(6)
	v_mfma_f32_32x32x16_bf16 v[2:17], v[66:69], v[204:207], v[2:17]
	v_exp_f32_e32 v196, v102
	v_exp_f32_e32 v197, v103
	v_exp_f32_e32 v198, v104
	v_exp_f32_e32 v199, v105
	s_waitcnt lgkmcnt(4)
	v_mfma_f32_32x32x16_bf16 v[2:17], v[70:73], v[208:211], v[2:17]
	v_exp_f32_e32 v200, v106
	v_exp_f32_e32 v201, v107
	v_exp_f32_e32 v202, v108
	v_exp_f32_e32 v203, v109
	v_exp_f32_e32 v204, v110
	v_exp_f32_e32 v205, v111
	s_waitcnt lgkmcnt(2)
	v_mfma_f32_32x32x16_bf16 v[2:17], v[74:77], v[212:215], v[2:17]
	v_exp_f32_e32 v206, v112
	v_exp_f32_e32 v207, v113
	v_fmamk_f32 v208, v95, 0x3e38aa3b, v148
	v_fmamk_f32 v209, v96, 0x3e38aa3b, v148
	v_fmac_f32_e32 v148, 0x3e38aa3b, v97
	s_waitcnt lgkmcnt(0)
	v_mfma_f32_32x32x16_bf16 v[2:17], v[78:81], v[216:219], v[2:17]
	v_add_u32_e32 v245, s101, v169
	v_add_u32_e32 v246, s101, v170
	v_add_u32_e32 v247, s101, v171
	v_add_u32_e32 v244, s101, v172
	v_cmp_gt_f32_e32 vcc, 1.0, v132
	s_cbranch_vccz .LBB0_774
	s_and_saveexec_b64 s[10:11], s[40:41]
	ds_write_b32 v162, v132 offset:128
	s_or_b64 exec, exec, s[10:11]
	s_waitcnt lgkmcnt(0)
	v_add_u32_e32 v67, s18, v140
	ds_read_b128 v[68:71], v67 offset:224
	ds_read_b128 v[72:75], v67 offset:192
	ds_read_b128 v[76:79], v67 offset:160
	ds_read_b128 v[134:137], v67 offset:128
	s_waitcnt lgkmcnt(0)
	v_pk_mul_f32 v[30:31], v[30:31], v[68:69]
	v_pk_mul_f32 v[26:27], v[26:27], v[72:73]
	v_pk_mul_f32 v[22:23], v[22:23], v[76:77]
	v_pk_mul_f32 v[32:33], v[32:33], v[70:71]
	v_pk_mul_f32 v[28:29], v[28:29], v[74:75]
	v_pk_mul_f32 v[24:25], v[24:25], v[78:79]
	v_pk_mul_f32 v[20:21], v[20:21], v[136:137]
	v_pk_mul_f32 v[18:19], v[18:19], v[134:135]
	v_pk_mul_f32 v[62:63], v[62:63], v[68:69]
	v_pk_mul_f32 v[58:59], v[58:59], v[72:73]
	v_pk_mul_f32 v[54:55], v[54:55], v[76:77]
	v_pk_mul_f32 v[64:65], v[64:65], v[70:71]
	v_pk_mul_f32 v[60:61], v[60:61], v[74:75]
	v_pk_mul_f32 v[56:57], v[56:57], v[78:79]
	v_pk_mul_f32 v[52:53], v[52:53], v[136:137]
	v_pk_mul_f32 v[50:51], v[50:51], v[134:135]
	v_pk_mul_f32 v[46:47], v[46:47], v[68:69]
	v_pk_mul_f32 v[42:43], v[42:43], v[72:73]
	v_pk_mul_f32 v[38:39], v[38:39], v[76:77]
	v_pk_mul_f32 v[48:49], v[48:49], v[70:71]
	v_pk_mul_f32 v[44:45], v[44:45], v[74:75]
	v_pk_mul_f32 v[40:41], v[40:41], v[78:79]
	v_pk_mul_f32 v[36:37], v[36:37], v[136:137]
	v_pk_mul_f32 v[34:35], v[34:35], v[134:135]
	v_pk_mul_f32 v[14:15], v[14:15], v[68:69]
	v_pk_mul_f32 v[10:11], v[10:11], v[72:73]
	v_pk_mul_f32 v[6:7], v[6:7], v[76:77]
	v_pk_mul_f32 v[16:17], v[16:17], v[70:71]
	v_pk_mul_f32 v[12:13], v[12:13], v[74:75]
	v_pk_mul_f32 v[8:9], v[8:9], v[78:79]
	v_pk_mul_f32 v[4:5], v[4:5], v[136:137]
	v_pk_mul_f32 v[2:3], v[2:3], v[134:135]
; #define SBAR() __builtin_amdgcn_sched_barrier(0)
; __device__ __forceinline__ void finishSM(f32x16& p0, f32x16& p1, float alpha, float& l_reg, bf16x8& pa0, bf16x8& pa1, bf16x8& pa2, bf16x8& pa3) {
;   for (int r = 0; r < 16; ++r) p1[r] = __builtin_amdgcn_exp2f(p1[r]);
;   float ps = 0; for (int r = 0; r < 16; ++r) ps += p0[r]; for (int r = 0; r < 16; ++r) ps += p1[r];
;   { auto rr = __builtin_amdgcn_permlane32_swap(__float_as_uint(ps), __float_as_uint(ps), false, false);
;     ps = __uint_as_float(rr[0]) + __uint_as_float(rr[1]); }
;   l_reg = l_reg * alpha + ps;
;     ...
;   PK4(p0, 0, pa0); PK4(p0, 8, pa1); PK4(p1, 0, pa2); PK4(p1, 8, pa3);
;     ...
; }
; __device__ __forceinline__ void kload(bf16x8 (&kf)[8], const char* Ks, int r32, int hi, int sb) {
; #pragma unroll
;   for (int d0 = 0; d0 < 4; ++d0) { const int cb = sb + (d0 * 16 + hi * 8) * 2;
;     kf[2 * d0] = *reinterpret_cast<const bf16x8*>(Ks + KSWZ(r32, cb)); kf[2 * d0 + 1] = *reinterpret_cast<const bf16x8*>(Ks + KSWZ(32 + r32, cb)); }
; }
; __device__ __forceinline__ void kmma(f32x16& p0, f32x16& p1, const bf16x8 (&kf)[8], const bf16x8* qr) {
;   asm volatile("s_waitcnt lgkmcnt(0)" ::: "memory"); SBAR();
;   p0 = f32x16{}; p1 = f32x16{};
; #pragma unroll
;   for (int d0 = 0; d0 < 4; ++d0) { p0 = __builtin_amdgcn_mfma_f32_32x32x16_bf16(kf[2 * d0], qr[d0], p0, 0, 0, 0); p1 = __builtin_amdgcn_mfma_f32_32x32x16_bf16(kf[2 * d0 + 1], qr[d0], p1, 0, 0, 0); }
; }
; __device__ __forceinline__ void qkt(f32x16& p0, f32x16& p1, const char* Ks, const bf16x8* qr, int r32, int hi, int sb) {
;   bf16x8 kf[8]; kload(kf, Ks, r32, hi, sb); SBAR(); kmma(p0, p1, kf, qr);
.LBB0_774:
	s_waitcnt vmcnt(4)
	s_barrier
	ds_read_b128 v[66:69], v245
	ds_read_b128 v[70:73], v245 offset:8192
	ds_read_b128 v[98:101], v246
	ds_read_b128 v[102:105], v246 offset:8192
	v_exp_f32_e32 v210, v82
	v_exp_f32_e32 v211, v83
	v_exp_f32_e32 v212, v84
	v_exp_f32_e32 v213, v85
	v_exp_f32_e32 v214, v86
	v_exp_f32_e32 v215, v87
	v_add_f32_e32 v216, 0, v192
	v_add_f32_e32 v216, v193, v216
	v_add_f32_e32 v216, v194, v216
	v_add_f32_e32 v216, v195, v216
	v_exp_f32_e32 v149, v149
	v_exp_f32_e32 v150, v150
	v_exp_f32_e32 v151, v151
	v_exp_f32_e32 v186, v186
	v_exp_f32_e32 v187, v187
	v_exp_f32_e32 v188, v188
	s_waitcnt lgkmcnt(3)
	v_mfma_f32_32x32x16_bf16 v[82:97], v[66:69], v[126:129], 0
	v_exp_f32_e32 v189, v189
	v_exp_f32_e32 v208, v208
	ds_read_b128 v[106:109], v247
	v_exp_f32_e32 v209, v209
	ds_read_b128 v[110:113], v247 offset:8192
	v_exp_f32_e32 v148, v148
	ds_read_b128 v[134:137], v244
	ds_read_b128 v[174:177], v244 offset:8192
	s_waitcnt lgkmcnt(6)
	v_mfma_f32_32x32x16_bf16 v[66:81], v[70:73], v[126:129], 0
	v_add_f32_e32 v255, v196, v216
	s_and_b32 s46, s13, 0xc000
	v_add_f32_e32 v255, v197, v255
	v_add_u32_e32 v244, s46, v164
	v_add_f32_e32 v255, v198, v255
	ds_read_b64_tr_b16 v[228:229], v244 offset:0
	v_add_f32_e32 v255, v199, v255
	ds_read_b64_tr_b16 v[230:231], v244 offset:0x800
	v_add_f32_e32 v255, v200, v255
	ds_read_b64_tr_b16 v[232:233], v244 offset:0x1000
	ds_read_b64_tr_b16 v[234:235], v244 offset:0x1800
	s_waitcnt lgkmcnt(9)
	v_mfma_f32_32x32x16_bf16 v[82:97], v[98:101], v[122:125], v[82:97]
	v_add_f32_e32 v255, v201, v255
	ds_read_b64_tr_b16 v[236:237], v244 offset:0x2000
	v_add_f32_e32 v255, v202, v255
	ds_read_b64_tr_b16 v[238:239], v244 offset:0x2800
	v_add_f32_e32 v255, v203, v255
	ds_read_b64_tr_b16 v[240:241], v244 offset:0x3000
	v_add_f32_e32 v255, v204, v255
	ds_read_b64_tr_b16 v[242:243], v244 offset:0x3800
	s_add_i32 s46, s12, 3
	s_cmpk_lt_u32 s12, 0x7d
	s_waitcnt lgkmcnt(12)
	v_mfma_f32_32x32x16_bf16 v[66:81], v[102:105], v[122:125], v[66:81]
	v_add_f32_e32 v255, v205, v255
	s_cselect_b64 s[42:43], -1, 0
	v_add_f32_e32 v255, v206, v255
	s_and_b64 s[44:45], s[42:43], exec
	v_add_f32_e32 v255, v207, v255
	s_cselect_b32 s44, 0, 0xffffff80
	v_add_f32_e32 v255, v210, v255
	s_add_i32 s58, s46, s44
	v_add_f32_e32 v255, v211, v255
	s_and_b64 s[42:43], s[42:43], exec
	s_cselect_b32 s43, s9, s30
	s_waitcnt lgkmcnt(11)
	v_mfma_f32_32x32x16_bf16 v[82:97], v[106:109], v[118:121], v[82:97]
	v_add_f32_e32 v255, v212, v255
	s_cselect_b32 s42, s8, s26
	v_add_f32_e32 v255, v213, v255
	s_lshl_b64 s[44:45], s[58:59], 17
	v_add_f32_e32 v255, v214, v255
	s_lshl_b64 s[42:43], s[42:43], 11
	v_add_f32_e32 v255, v215, v255
	s_add_u32 s44, s44, s42
	s_addc_u32 s45, s45, s43
	s_add_u32 s42, s20, s44
	s_waitcnt lgkmcnt(10)
	v_mfma_f32_32x32x16_bf16 v[66:81], v[110:113], v[118:121], v[66:81]
	v_add_f32_e32 v255, v149, v255
	s_addc_u32 s43, s21, s45
	v_add_f32_e32 v255, v150, v255
	s_add_u32 s44, s22, s44
	v_add_f32_e32 v255, v151, v255
	s_mul_i32 s47, s46, 0xab
	v_add_f32_e32 v255, v186, v255
	s_addc_u32 s45, s23, s45
	v_add_f32_e32 v255, v187, v255
	s_bfe_u32 s47, s47, 0x70009
	s_mul_i32 s47, s47, 3
	s_waitcnt lgkmcnt(9)
	v_mfma_f32_32x32x16_bf16 v[82:97], v[134:137], v[114:117], v[82:97]
	v_add_f32_e32 v255, v188, v255
	s_sub_i32 s46, s46, s47
	v_add_f32_e32 v255, v189, v255
	s_and_b32 s46, s46, 0xff
	v_add_f32_e32 v255, v208, v255
	s_lshl_b32 s46, s46, 14
	s_mov_b32 s101, s46
	v_add_f32_e32 v255, v209, v255
	s_add_i32 s46, s46, s27
	v_add_f32_e32 v99, v148, v255
	s_and_b32 s47, s36, 0xc000
	s_add_i32 s47, s47, s31
	s_cmpk_gt_u32 s12, 0x80
	s_cselect_b64 s[10:11], -1, 0
	s_and_b64 vcc, exec, s[10:11]
	s_cbranch_vccnz .LBB0_776
	v_lshl_add_u64 v[246:247], s[42:43], 0, v[146:147]
	s_mov_b32 m0, s46
	s_nop 0
	global_load_lds_dwordx4 v[246:247], off
	v_lshl_add_u64 v[246:247], s[44:45], 0, v[142:143]
	s_mov_b32 m0, s47
	s_nop 0
	global_load_lds_dwordx4 v[246:247], off
	v_lshl_add_u64 v[246:247], s[42:43], 0, v[144:145]
	s_add_i32 m0, s46, 0x2000
	s_nop 0
	global_load_lds_dwordx4 v[246:247], off
	v_lshl_add_u64 v[246:247], s[44:45], 0, v[154:155]
	s_add_i32 m0, s47, 0x2000
	s_nop 0
	global_load_lds_dwordx4 v[246:247], off
